# v110 + non-temporal stores also for the mix / memo / fo GEMM outputs that the row passes read once
# baseline (speedup 1.0000x reference)
; __device__ __forceinline__ unsigned cvtpk(float lo, float hi) { f32x2_t v = {lo, hi}; bf16x2_t b = __builtin_convertvector(v, bf16x2_t); return __builtin_bit_cast(unsigned, b); }
; template <int mode>
; __device__ __forceinline__ void epilogue(f32x4 (&acc)[2][2][4][2], const GUnit& u, int wr, int wc, int fr, int fq, LAS unsigned char* lds) {
;     if (mode == 0) {
;         bf16_t* base = (bf16_t*)u.C; const float sc = u.scale;
; #pragma unroll
;         for (int ai = 0; ai < 2; ++ai)
; #pragma unroll
;             for (int m = 0; m < 4; ++m) {
;                 bf16_t* rowp = base + (size_t)ai * u.SA + (size_t)(wr * 64 + m * 16 + fr) * u.SR + (wc >> 1) * u.SX + (wc & 1) * 32 + 8 * fq;
; #pragma unroll
;                 for (int bj = 0; bj < 2; ++bj) {
;                     const f32x4 v0 = acc[ai][bj][m][0] * sc, v1 = acc[ai][bj][m][1] * sc;
;                     u32x4 w; w.x = cvtpk(v0[0], v0[1]); w.y = cvtpk(v0[2], v0[3]); w.z = cvtpk(v1[0], v1[1]); w.w = cvtpk(v1[2], v1[3]);
;                     *(u32x4*)(rowp + (size_t)bj * u.SB) = w;
;                 }
;             }
.LBB0_403:
	s_add_u32 s14, s20, 0x80000
	s_addc_u32 s15, s21, 0
	v_lshl_add_u64 v[154:155], s[20:21], 0, v[142:143]
	v_cvt_pk_bf16_f32 v68, v68, v69
	v_cvt_pk_bf16_f32 v69, v70, v71
	v_cvt_pk_bf16_f32 v70, v64, v65
	v_lshl_add_u64 v[64:65], s[14:15], 0, v[142:143]
	v_lshl_add_u64 v[154:155], v[154:155], 0, s[4:5]
	s_mov_b32 s19, s5
	v_cvt_pk_bf16_f32 v108, v108, v109
	v_cvt_pk_bf16_f32 v109, v110, v111
	v_cvt_pk_bf16_f32 v110, v104, v105
	v_lshl_add_u64 v[104:105], s[20:21], 0, v[144:145]
	v_lshl_add_u64 v[64:65], v[64:65], 0, s[4:5]
	v_cvt_pk_bf16_f32 v44, v44, v45
	v_cvt_pk_bf16_f32 v45, v46, v47
	v_cvt_pk_bf16_f32 v46, v40, v41
	v_lshl_add_u64 v[40:41], s[14:15], 0, v[144:145]
	v_lshl_add_u64 v[154:155], v[154:155], 0, s[18:19]
	v_lshl_add_u64 v[104:105], v[104:105], 0, s[4:5]
	v_cvt_pk_bf16_f32 v92, v92, v93
	v_cvt_pk_bf16_f32 v93, v94, v95
	v_cvt_pk_bf16_f32 v94, v88, v89
	v_lshl_add_u64 v[88:89], s[20:21], 0, v[146:147]
	v_lshl_add_u64 v[64:65], v[64:65], 0, s[18:19]
	v_lshl_add_u64 v[40:41], v[40:41], 0, s[4:5]
	v_cvt_pk_bf16_f32 v28, v28, v29
	v_cvt_pk_bf16_f32 v29, v30, v31
	v_cvt_pk_bf16_f32 v30, v24, v25
	v_lshl_add_u64 v[24:25], s[14:15], 0, v[146:147]
	v_lshl_add_u64 v[154:155], v[154:155], 0, v[136:137]
	v_cvt_pk_bf16_f32 v111, v106, v107
	v_lshl_add_u64 v[104:105], v[104:105], 0, s[18:19]
	v_lshl_add_u64 v[88:89], v[88:89], 0, s[4:5]
	v_cvt_pk_bf16_f32 v76, v76, v77
	v_cvt_pk_bf16_f32 v77, v78, v79
	v_cvt_pk_bf16_f32 v78, v72, v73
	v_lshl_add_u64 v[72:73], s[20:21], 0, v[148:149]
	v_lshl_add_u64 v[64:65], v[64:65], 0, v[136:137]
	v_cvt_pk_bf16_f32 v47, v42, v43
	v_lshl_add_u64 v[40:41], v[40:41], 0, s[18:19]
	v_lshl_add_u64 v[24:25], v[24:25], 0, s[4:5]
	v_cvt_pk_bf16_f32 v12, v12, v13
	v_cvt_pk_bf16_f32 v13, v14, v15
	v_cvt_pk_bf16_f32 v14, v8, v9
	v_lshl_add_u64 v[8:9], s[14:15], 0, v[148:149]
	global_store_dwordx4 v[154:155], v[108:111], off offset:256 nt
	v_cvt_pk_bf16_f32 v95, v90, v91
	v_lshl_add_u64 v[88:89], v[88:89], 0, s[18:19]
	v_lshl_add_u64 v[108:109], v[104:105], 0, v[136:137]
	v_lshl_add_u64 v[72:73], v[72:73], 0, s[4:5]
	global_store_dwordx4 v[64:65], v[44:47], off offset:256 nt
	v_cvt_pk_bf16_f32 v31, v26, v27
	v_lshl_add_u64 v[24:25], v[24:25], 0, s[18:19]
	v_lshl_add_u64 v[44:45], v[40:41], 0, v[136:137]
	v_lshl_add_u64 v[8:9], v[8:9], 0, s[4:5]
	global_store_dwordx4 v[108:109], v[92:95], off offset:256 nt
	v_cvt_pk_bf16_f32 v79, v74, v75
	v_lshl_add_u64 v[72:73], v[72:73], 0, s[18:19]
	v_lshl_add_u64 v[92:93], v[88:89], 0, v[136:137]
	global_store_dwordx4 v[44:45], v[28:31], off offset:256 nt
	v_cvt_pk_bf16_f32 v15, v10, v11
	v_lshl_add_u64 v[8:9], v[8:9], 0, s[18:19]
	v_lshl_add_u64 v[28:29], v[24:25], 0, v[136:137]
	v_cvt_pk_bf16_f32 v124, v124, v125
	v_cvt_pk_bf16_f32 v125, v126, v127
	v_cvt_pk_bf16_f32 v126, v120, v121
	v_cvt_pk_bf16_f32 v127, v122, v123
	v_cvt_pk_bf16_f32 v104, v116, v117
	v_cvt_pk_bf16_f32 v105, v118, v119
	v_cvt_pk_bf16_f32 v106, v112, v113
	v_cvt_pk_bf16_f32 v107, v114, v115
	v_cvt_pk_bf16_f32 v88, v100, v101
	v_cvt_pk_bf16_f32 v89, v102, v103
	v_cvt_pk_bf16_f32 v90, v96, v97
	v_cvt_pk_bf16_f32 v91, v98, v99
	global_store_dwordx4 v[92:93], v[76:79], off offset:256 nt
	v_cvt_pk_bf16_f32 v74, v80, v81
	v_cvt_pk_bf16_f32 v75, v82, v83
	v_lshl_add_u64 v[76:77], v[72:73], 0, v[136:137]
	v_cvt_pk_bf16_f32 v72, v84, v85
	v_cvt_pk_bf16_f32 v73, v86, v87
	v_cvt_pk_bf16_f32 v71, v66, v67
	v_cvt_pk_bf16_f32 v60, v60, v61
	v_cvt_pk_bf16_f32 v61, v62, v63
	v_cvt_pk_bf16_f32 v62, v56, v57
	v_cvt_pk_bf16_f32 v63, v58, v59
	v_cvt_pk_bf16_f32 v40, v52, v53
	v_cvt_pk_bf16_f32 v41, v54, v55
	v_cvt_pk_bf16_f32 v42, v48, v49
	v_cvt_pk_bf16_f32 v43, v50, v51
	v_cvt_pk_bf16_f32 v24, v36, v37
	v_cvt_pk_bf16_f32 v25, v38, v39
	v_cvt_pk_bf16_f32 v26, v32, v33
	v_cvt_pk_bf16_f32 v27, v34, v35
	global_store_dwordx4 v[28:29], v[12:15], off offset:256 nt
	v_cvt_pk_bf16_f32 v10, v16, v17
	v_cvt_pk_bf16_f32 v11, v18, v19
	v_lshl_add_u64 v[12:13], v[8:9], 0, v[136:137]
	v_cvt_pk_bf16_f32 v8, v20, v21
	v_cvt_pk_bf16_f32 v9, v22, v23
	v_cvt_pk_bf16_f32 v4, v4, v5
	v_cvt_pk_bf16_f32 v5, v6, v7
	v_cvt_pk_bf16_f32 v6, v0, v1
	v_cvt_pk_bf16_f32 v7, v2, v3
	s_andn2_b64 vcc, exec, s[38:39]
	s_mov_b64 s[14:15], -1
	global_store_dwordx4 v[154:155], v[124:127], off nt
	global_store_dwordx4 v[108:109], v[104:107], off nt
	global_store_dwordx4 v[92:93], v[88:91], off nt
	global_store_dwordx4 v[76:77], v[72:75], off nt
	global_store_dwordx4 v[76:77], v[68:71], off offset:256 nt
	global_store_dwordx4 v[64:65], v[60:63], off nt
	global_store_dwordx4 v[44:45], v[40:43], off nt
	global_store_dwordx4 v[28:29], v[24:27], off nt
	global_store_dwordx4 v[12:13], v[8:11], off nt
	global_store_dwordx4 v[12:13], v[4:7], off offset:256 nt
	s_cbranch_vccnz .LBB0_392
	s_andn2_b64 vcc, exec, s[6:7]
	s_cbranch_vccnz .LBB0_391
	s_barrier
	s_branch .LBB0_391

; __device__ __forceinline__ unsigned cvtpk(float lo, float hi) { f32x2_t v = {lo, hi}; bf16x2_t b = __builtin_convertvector(v, bf16x2_t); return __builtin_bit_cast(unsigned, b); }
; template <int mode>
; __device__ __forceinline__ void epilogue(f32x4 (&acc)[2][2][4][2], const GUnit& u, int wr, int wc, int fr, int fq, LAS unsigned char* lds) {
;     if (mode == 0) {
;         bf16_t* base = (bf16_t*)u.C; const float sc = u.scale;
; #pragma unroll
;         for (int ai = 0; ai < 2; ++ai)
; #pragma unroll
;             for (int m = 0; m < 4; ++m) {
;                 bf16_t* rowp = base + (size_t)ai * u.SA + (size_t)(wr * 64 + m * 16 + fr) * u.SR + (wc >> 1) * u.SX + (wc & 1) * 32 + 8 * fq;
; #pragma unroll
;                 for (int bj = 0; bj < 2; ++bj) {
;                     const f32x4 v0 = acc[ai][bj][m][0] * sc, v1 = acc[ai][bj][m][1] * sc;
;                     u32x4 w; w.x = cvtpk(v0[0], v0[1]); w.y = cvtpk(v0[2], v0[3]); w.z = cvtpk(v1[0], v1[1]); w.w = cvtpk(v1[2], v1[3]);
;                     *(u32x4*)(rowp + (size_t)bj * u.SB) = w;
;                 }
;             }
.LBB0_700:
	s_add_u32 s16, s20, 0x80000
	s_addc_u32 s17, s21, 0
	v_lshl_add_u64 v[156:157], s[20:21], 0, v[144:145]
	v_cvt_pk_bf16_f32 v68, v68, v69
	v_cvt_pk_bf16_f32 v69, v70, v71
	v_cvt_pk_bf16_f32 v70, v64, v65
	v_lshl_add_u64 v[64:65], s[16:17], 0, v[144:145]
	v_lshl_add_u64 v[156:157], v[156:157], 0, s[6:7]
	s_mov_b32 s19, s7
	v_cvt_pk_bf16_f32 v108, v108, v109
	v_cvt_pk_bf16_f32 v109, v110, v111
	v_cvt_pk_bf16_f32 v110, v104, v105
	v_lshl_add_u64 v[104:105], s[20:21], 0, v[146:147]
	v_lshl_add_u64 v[64:65], v[64:65], 0, s[6:7]
	v_cvt_pk_bf16_f32 v44, v44, v45
	v_cvt_pk_bf16_f32 v45, v46, v47
	v_cvt_pk_bf16_f32 v46, v40, v41
	v_lshl_add_u64 v[40:41], s[16:17], 0, v[146:147]
	v_lshl_add_u64 v[156:157], v[156:157], 0, s[18:19]
	v_lshl_add_u64 v[104:105], v[104:105], 0, s[6:7]
	v_cvt_pk_bf16_f32 v92, v92, v93
	v_cvt_pk_bf16_f32 v93, v94, v95
	v_cvt_pk_bf16_f32 v94, v88, v89
	v_lshl_add_u64 v[88:89], s[20:21], 0, v[148:149]
	v_lshl_add_u64 v[64:65], v[64:65], 0, s[18:19]
	v_lshl_add_u64 v[40:41], v[40:41], 0, s[6:7]
	v_cvt_pk_bf16_f32 v28, v28, v29
	v_cvt_pk_bf16_f32 v29, v30, v31
	v_cvt_pk_bf16_f32 v30, v24, v25
	v_lshl_add_u64 v[24:25], s[16:17], 0, v[148:149]
	v_lshl_add_u64 v[156:157], v[156:157], 0, v[138:139]
	v_cvt_pk_bf16_f32 v111, v106, v107
	v_lshl_add_u64 v[104:105], v[104:105], 0, s[18:19]
	v_lshl_add_u64 v[88:89], v[88:89], 0, s[6:7]
	v_cvt_pk_bf16_f32 v76, v76, v77
	v_cvt_pk_bf16_f32 v77, v78, v79
	v_cvt_pk_bf16_f32 v78, v72, v73
	v_lshl_add_u64 v[72:73], s[20:21], 0, v[150:151]
	v_lshl_add_u64 v[64:65], v[64:65], 0, v[138:139]
	v_cvt_pk_bf16_f32 v47, v42, v43
	v_lshl_add_u64 v[40:41], v[40:41], 0, s[18:19]
	v_lshl_add_u64 v[24:25], v[24:25], 0, s[6:7]
	v_cvt_pk_bf16_f32 v12, v12, v13
	v_cvt_pk_bf16_f32 v13, v14, v15
	v_cvt_pk_bf16_f32 v14, v8, v9
	v_lshl_add_u64 v[8:9], s[16:17], 0, v[150:151]
	global_store_dwordx4 v[156:157], v[108:111], off offset:256 nt
	v_cvt_pk_bf16_f32 v95, v90, v91
	v_lshl_add_u64 v[88:89], v[88:89], 0, s[18:19]
	v_lshl_add_u64 v[108:109], v[104:105], 0, v[138:139]
	v_lshl_add_u64 v[72:73], v[72:73], 0, s[6:7]
	global_store_dwordx4 v[64:65], v[44:47], off offset:256 nt
	v_cvt_pk_bf16_f32 v31, v26, v27
	v_lshl_add_u64 v[24:25], v[24:25], 0, s[18:19]
	v_lshl_add_u64 v[44:45], v[40:41], 0, v[138:139]
	v_lshl_add_u64 v[8:9], v[8:9], 0, s[6:7]
	global_store_dwordx4 v[108:109], v[92:95], off offset:256 nt
	v_cvt_pk_bf16_f32 v79, v74, v75
	v_lshl_add_u64 v[72:73], v[72:73], 0, s[18:19]
	v_lshl_add_u64 v[92:93], v[88:89], 0, v[138:139]
	global_store_dwordx4 v[44:45], v[28:31], off offset:256 nt
	v_cvt_pk_bf16_f32 v15, v10, v11
	v_lshl_add_u64 v[8:9], v[8:9], 0, s[18:19]
	v_lshl_add_u64 v[28:29], v[24:25], 0, v[138:139]
	v_cvt_pk_bf16_f32 v124, v124, v125
	v_cvt_pk_bf16_f32 v125, v126, v127
	v_cvt_pk_bf16_f32 v126, v120, v121
	v_cvt_pk_bf16_f32 v127, v122, v123
	v_cvt_pk_bf16_f32 v104, v116, v117
	v_cvt_pk_bf16_f32 v105, v118, v119
	v_cvt_pk_bf16_f32 v106, v112, v113
	v_cvt_pk_bf16_f32 v107, v114, v115
	v_cvt_pk_bf16_f32 v88, v100, v101
	v_cvt_pk_bf16_f32 v89, v102, v103
	v_cvt_pk_bf16_f32 v90, v96, v97
	v_cvt_pk_bf16_f32 v91, v98, v99
	global_store_dwordx4 v[92:93], v[76:79], off offset:256 nt
	v_cvt_pk_bf16_f32 v74, v80, v81
	v_cvt_pk_bf16_f32 v75, v82, v83
	v_lshl_add_u64 v[76:77], v[72:73], 0, v[138:139]
	v_cvt_pk_bf16_f32 v72, v84, v85
	v_cvt_pk_bf16_f32 v73, v86, v87
	v_cvt_pk_bf16_f32 v71, v66, v67
	v_cvt_pk_bf16_f32 v60, v60, v61
	v_cvt_pk_bf16_f32 v61, v62, v63
	v_cvt_pk_bf16_f32 v62, v56, v57
	v_cvt_pk_bf16_f32 v63, v58, v59
	v_cvt_pk_bf16_f32 v40, v52, v53
	v_cvt_pk_bf16_f32 v41, v54, v55
	v_cvt_pk_bf16_f32 v42, v48, v49
	v_cvt_pk_bf16_f32 v43, v50, v51
	v_cvt_pk_bf16_f32 v24, v36, v37
	v_cvt_pk_bf16_f32 v25, v38, v39
	v_cvt_pk_bf16_f32 v26, v32, v33
	v_cvt_pk_bf16_f32 v27, v34, v35
	global_store_dwordx4 v[28:29], v[12:15], off offset:256 nt
	v_cvt_pk_bf16_f32 v10, v16, v17
	v_cvt_pk_bf16_f32 v11, v18, v19
	v_lshl_add_u64 v[12:13], v[8:9], 0, v[138:139]
	v_cvt_pk_bf16_f32 v8, v20, v21
	v_cvt_pk_bf16_f32 v9, v22, v23
	v_cvt_pk_bf16_f32 v4, v4, v5
	v_cvt_pk_bf16_f32 v5, v6, v7
	v_cvt_pk_bf16_f32 v6, v0, v1
	v_cvt_pk_bf16_f32 v7, v2, v3
	s_andn2_b64 vcc, exec, s[36:37]
	s_mov_b64 s[16:17], -1
	global_store_dwordx4 v[156:157], v[124:127], off nt
	global_store_dwordx4 v[108:109], v[104:107], off nt
	global_store_dwordx4 v[92:93], v[88:91], off nt
	global_store_dwordx4 v[76:77], v[72:75], off nt
	global_store_dwordx4 v[76:77], v[68:71], off offset:256 nt
	global_store_dwordx4 v[64:65], v[60:63], off nt
	global_store_dwordx4 v[44:45], v[40:43], off nt
	global_store_dwordx4 v[28:29], v[24:27], off nt
	global_store_dwordx4 v[12:13], v[8:11], off nt
	global_store_dwordx4 v[12:13], v[4:7], off offset:256 nt
	s_cbranch_vccnz .LBB0_689
	s_andn2_b64 vcc, exec, s[8:9]
	s_cbranch_vccnz .LBB0_688
	s_barrier
	s_branch .LBB0_688

; __device__ __forceinline__ unsigned cvtpk(float lo, float hi) { f32x2_t v = {lo, hi}; bf16x2_t b = __builtin_convertvector(v, bf16x2_t); return __builtin_bit_cast(unsigned, b); }
; template <int mode>
; __device__ __forceinline__ void epilogue(f32x4 (&acc)[2][2][4][2], const GUnit& u, int wr, int wc, int fr, int fq, LAS unsigned char* lds) {
;     if (mode == 0) {
;         bf16_t* base = (bf16_t*)u.C; const float sc = u.scale;
; #pragma unroll
;         for (int ai = 0; ai < 2; ++ai)
; #pragma unroll
;             for (int m = 0; m < 4; ++m) {
;                 bf16_t* rowp = base + (size_t)ai * u.SA + (size_t)(wr * 64 + m * 16 + fr) * u.SR + (wc >> 1) * u.SX + (wc & 1) * 32 + 8 * fq;
; #pragma unroll
;                 for (int bj = 0; bj < 2; ++bj) {
;                     const f32x4 v0 = acc[ai][bj][m][0] * sc, v1 = acc[ai][bj][m][1] * sc;
;                     u32x4 w; w.x = cvtpk(v0[0], v0[1]); w.y = cvtpk(v0[2], v0[3]); w.z = cvtpk(v1[0], v1[1]); w.w = cvtpk(v1[2], v1[3]);
;                     *(u32x4*)(rowp + (size_t)bj * u.SB) = w;
;                 }
;             }
.LBB0_899:
	v_lshl_add_u64 v[156:157], s[16:17], 0, v[144:145]
	v_cvt_pk_bf16_f32 v108, v108, v109
	v_cvt_pk_bf16_f32 v109, v110, v111
	v_cvt_pk_bf16_f32 v110, v104, v105
	v_lshl_add_u64 v[104:105], s[16:17], 0, v[146:147]
	v_cvt_pk_bf16_f32 v92, v92, v93
	v_cvt_pk_bf16_f32 v93, v94, v95
	v_cvt_pk_bf16_f32 v94, v88, v89
	v_lshl_add_u64 v[88:89], s[16:17], 0, v[148:149]
	v_cvt_pk_bf16_f32 v76, v76, v77
	v_cvt_pk_bf16_f32 v77, v78, v79
	v_cvt_pk_bf16_f32 v78, v72, v73
	v_lshl_add_u64 v[72:73], s[16:17], 0, v[150:151]
	s_add_u32 s16, s16, 0x80000
	s_addc_u32 s17, s17, 0
	v_cvt_pk_bf16_f32 v68, v68, v69
	v_cvt_pk_bf16_f32 v69, v70, v71
	v_cvt_pk_bf16_f32 v70, v64, v65
	v_lshl_add_u64 v[64:65], s[16:17], 0, v[144:145]
	v_lshl_add_u64 v[156:157], v[156:157], 0, s[6:7]
	s_mov_b32 s15, s7
	v_lshl_add_u64 v[64:65], v[64:65], 0, s[6:7]
	v_cvt_pk_bf16_f32 v44, v44, v45
	v_cvt_pk_bf16_f32 v45, v46, v47
	v_cvt_pk_bf16_f32 v46, v40, v41
	v_lshl_add_u64 v[40:41], s[16:17], 0, v[146:147]
	v_lshl_add_u64 v[156:157], v[156:157], 0, s[14:15]
	v_lshl_add_u64 v[104:105], v[104:105], 0, s[6:7]
	v_lshl_add_u64 v[64:65], v[64:65], 0, s[14:15]
	v_lshl_add_u64 v[40:41], v[40:41], 0, s[6:7]
	v_cvt_pk_bf16_f32 v28, v28, v29
	v_cvt_pk_bf16_f32 v29, v30, v31
	v_cvt_pk_bf16_f32 v30, v24, v25
	v_lshl_add_u64 v[24:25], s[16:17], 0, v[148:149]
	v_lshl_add_u64 v[156:157], v[156:157], 0, v[138:139]
	v_cvt_pk_bf16_f32 v111, v106, v107
	v_lshl_add_u64 v[104:105], v[104:105], 0, s[14:15]
	v_lshl_add_u64 v[88:89], v[88:89], 0, s[6:7]
	v_lshl_add_u64 v[64:65], v[64:65], 0, v[138:139]
	v_cvt_pk_bf16_f32 v47, v42, v43
	v_lshl_add_u64 v[40:41], v[40:41], 0, s[14:15]
	v_lshl_add_u64 v[24:25], v[24:25], 0, s[6:7]
	v_cvt_pk_bf16_f32 v12, v12, v13
	v_cvt_pk_bf16_f32 v13, v14, v15
	v_cvt_pk_bf16_f32 v14, v8, v9
	v_lshl_add_u64 v[8:9], s[16:17], 0, v[150:151]
	global_store_dwordx4 v[156:157], v[108:111], off offset:256 nt
	v_cvt_pk_bf16_f32 v95, v90, v91
	v_lshl_add_u64 v[88:89], v[88:89], 0, s[14:15]
	v_lshl_add_u64 v[108:109], v[104:105], 0, v[138:139]
	v_lshl_add_u64 v[72:73], v[72:73], 0, s[6:7]
	global_store_dwordx4 v[64:65], v[44:47], off offset:256 nt
	v_cvt_pk_bf16_f32 v31, v26, v27
	v_lshl_add_u64 v[24:25], v[24:25], 0, s[14:15]
	v_lshl_add_u64 v[44:45], v[40:41], 0, v[138:139]
	v_lshl_add_u64 v[8:9], v[8:9], 0, s[6:7]
	global_store_dwordx4 v[108:109], v[92:95], off offset:256 nt
	v_cvt_pk_bf16_f32 v79, v74, v75
	v_lshl_add_u64 v[72:73], v[72:73], 0, s[14:15]
	v_lshl_add_u64 v[92:93], v[88:89], 0, v[138:139]
	global_store_dwordx4 v[44:45], v[28:31], off offset:256 nt
	v_cvt_pk_bf16_f32 v15, v10, v11
	v_lshl_add_u64 v[8:9], v[8:9], 0, s[14:15]
	v_lshl_add_u64 v[28:29], v[24:25], 0, v[138:139]
	v_cvt_pk_bf16_f32 v124, v124, v125
	v_cvt_pk_bf16_f32 v125, v126, v127
	v_cvt_pk_bf16_f32 v126, v120, v121
	v_cvt_pk_bf16_f32 v127, v122, v123
	v_cvt_pk_bf16_f32 v104, v116, v117
	v_cvt_pk_bf16_f32 v105, v118, v119
	v_cvt_pk_bf16_f32 v106, v112, v113
	v_cvt_pk_bf16_f32 v107, v114, v115
	v_cvt_pk_bf16_f32 v88, v100, v101
	v_cvt_pk_bf16_f32 v89, v102, v103
	v_cvt_pk_bf16_f32 v90, v96, v97
	v_cvt_pk_bf16_f32 v91, v98, v99
	global_store_dwordx4 v[92:93], v[76:79], off offset:256 nt
	v_cvt_pk_bf16_f32 v74, v80, v81
	v_cvt_pk_bf16_f32 v75, v82, v83
	v_lshl_add_u64 v[76:77], v[72:73], 0, v[138:139]
	v_cvt_pk_bf16_f32 v72, v84, v85
	v_cvt_pk_bf16_f32 v73, v86, v87
	v_cvt_pk_bf16_f32 v71, v66, v67
	v_cvt_pk_bf16_f32 v60, v60, v61
	v_cvt_pk_bf16_f32 v61, v62, v63
	v_cvt_pk_bf16_f32 v62, v56, v57
	v_cvt_pk_bf16_f32 v63, v58, v59
	v_cvt_pk_bf16_f32 v40, v52, v53
	v_cvt_pk_bf16_f32 v41, v54, v55
	v_cvt_pk_bf16_f32 v42, v48, v49
	v_cvt_pk_bf16_f32 v43, v50, v51
	v_cvt_pk_bf16_f32 v24, v36, v37
	v_cvt_pk_bf16_f32 v25, v38, v39
	v_cvt_pk_bf16_f32 v26, v32, v33
	v_cvt_pk_bf16_f32 v27, v34, v35
	global_store_dwordx4 v[28:29], v[12:15], off offset:256 nt
	v_cvt_pk_bf16_f32 v10, v16, v17
	v_cvt_pk_bf16_f32 v11, v18, v19
	v_lshl_add_u64 v[12:13], v[8:9], 0, v[138:139]
	v_cvt_pk_bf16_f32 v8, v20, v21
	v_cvt_pk_bf16_f32 v9, v22, v23
	v_cvt_pk_bf16_f32 v4, v4, v5
	v_cvt_pk_bf16_f32 v5, v6, v7
	v_cvt_pk_bf16_f32 v6, v0, v1
	v_cvt_pk_bf16_f32 v7, v2, v3
	s_andn2_b64 vcc, exec, s[18:19]
	s_mov_b64 s[16:17], -1
	global_store_dwordx4 v[156:157], v[124:127], off nt
	global_store_dwordx4 v[108:109], v[104:107], off nt
	global_store_dwordx4 v[92:93], v[88:91], off nt
	global_store_dwordx4 v[76:77], v[72:75], off nt
	global_store_dwordx4 v[76:77], v[68:71], off offset:256 nt
	global_store_dwordx4 v[64:65], v[60:63], off nt
	global_store_dwordx4 v[44:45], v[40:43], off nt
	global_store_dwordx4 v[28:29], v[24:27], off nt
	global_store_dwordx4 v[12:13], v[8:11], off nt
	global_store_dwordx4 v[12:13], v[4:7], off offset:256 nt
	s_cbranch_vccnz .LBB0_888
	s_andn2_b64 vcc, exec, s[8:9]
	s_cbranch_vccnz .LBB0_887
	s_barrier
	s_branch .LBB0_887
